# K-loop 4+4 DMA balance on top of static priority
# speedup vs baseline: 1.0167x; 1.0167x over previous
; #define PG8_STAGE(bufoff, gbase, voff) do { _Pragma("unroll") for (int _i = 0; _i < 2; ++_i) \
;         __builtin_amdgcn_global_load_lds((const unsigned*)((const char*)(gbase) + (voff)[_i]), (PG8_LAS unsigned*)(lds + (bufoff) + ldsw + _i * 8192), 16, 0, 0); } while (0)
; #define PG8_WAIT_V(n) asm volatile("s_waitcnt vmcnt(" #n ")" ::: "memory")
; #define PG8_BAR __builtin_amdgcn_s_barrier()
; template <class Epi, class Sched, bool ALIGN_EPI = false, bool SP2 = false>
; __device__ __forceinline__ void gemm_phase(PG8_LAS unsigned char* lds, const Gemm g, const Sched& S, const Epi& E, const int wid_) {
;     ...
;     for (int i = 0; i < 2; ++i) { int R, C; stage_rc(tid * 16 + i * 8192, R, C); const int Rb = Epi::PERM ? ((R & ~31) + perm32(R & 31)) : R;
;         voffA[i] = (unsigned)(R * g.lda + C) * 2u; voffB[i] = (unsigned)(Rb * g.ldb + C) * 2u; }
;     const size_t kstep = (size_t)(BK * 2);
;     const size_t hstepA = (size_t)HALF * g.lda * 2, hstepB = (size_t)HALF * g.ldb * 2;
;     const size_t tstepA = 2 * hstepA, tstepB = 2 * hstepB;
;     ...
;     const char* cA = (const char*)g.A + (size_t)cur.pm * tstepA; const char* cB = (const char*)g.Bt + (size_t)cur.pn * tstepB;
;     S.a_ready(cur);
;     if constexpr (SP2) {
;         PG8_STAGE(PG8_SB(0, 0), cB, voffB); PG8_STAGE(PG8_SB(0, 1), cB + hstepB, voffB); PG8_STAGE(PG8_SA(0, 0), cA, voffA); PG8_STAGE(PG8_SA(0, 1), cA + hstepA, voffA);
;         if (wr == 1) PG8_BAR;
;         PG8_WAIT_V(2); PG8_BAR;
;         PG8_STAGE(PG8_SB(1, 0), cB + kstep, voffB); PG8_STAGE(PG8_SA(1, 0), cA + kstep, voffA); PG8_STAGE(PG8_SB(1, 1), cB + hstepB + kstep, voffB);
.LBB0_363:
	s_andn2_b64 vcc, exec, s[4:5]
	s_cbranch_vccnz .LBB0_343
	s_lshl_b32 s83, s3, 10
	v_lshl_add_u32 v0, v18, 4, s83
	v_ashrrev_i32_e32 v1, 31, v0
	v_lshrrev_b32_e32 v1, 22, v1
	v_add_u32_e32 v1, v0, v1
	v_ashrrev_i32_e32 v1, 10, v1
	v_mul_i32_i24_e32 v2, 0x400, v1
	v_sub_u32_e32 v2, v0, v2
	v_lshrrev_b32_e32 v3, 4, v2
	v_bitop3_b32 v2, v3, v2, 32 bitop3:0x6c
	v_ashrrev_i32_e32 v4, 31, v2
	v_lshrrev_b32_e32 v4, 26, v4
	v_lshlrev_b32_e32 v3, 3, v1
	v_add_u32_e32 v4, v2, v4
	v_and_b32_e32 v3, -16, v3
	v_ashrrev_i32_e32 v5, 6, v4
	v_lshlrev_b32_e32 v1, 5, v1
	v_add_u32_e32 v3, v5, v3
	s_waitcnt vmcnt(0) lgkmcnt(0)
	v_and_b32_e32 v12, 32, v1
	v_and_b32_e32 v1, 0xc0, v4
	v_sub_u32_e32 v1, v2, v1
	v_lshlrev_b32_e32 v2, 1, v3
	v_lshrrev_b32_e32 v4, 2, v3
	v_and_b32_e32 v5, 3, v5
	s_mov_b32 s5, 0x7fffffe0
	v_ashrrev_i16_sdwa v1, v239, sext(v1) dst_sel:DWORD dst_unused:UNUSED_PAD src0_sel:DWORD src1_sel:BYTE_0
	v_and_b32_e32 v2, 24, v2
	v_and_b32_e32 v4, 4, v4
	v_and_or_b32 v5, v3, s5, v5
	v_bfe_i32 v13, v1, 0, 16
	v_or3_b32 v2, v5, v4, v2
	v_add_u32_e32 v1, v12, v13
	v_mul_lo_u32 v14, v3, s10
	v_mul_lo_u32 v2, v2, s24
	v_add_u32_e32 v0, 0x2000, v0
	v_add_lshl_u32 v140, v1, v14, 1
	v_add_lshl_u32 v142, v2, v1, 1
	v_ashrrev_i32_e32 v1, 31, v0
	v_lshrrev_b32_e32 v1, 22, v1
	v_add_u32_e32 v1, v0, v1
	v_ashrrev_i32_e32 v1, 10, v1
	v_mul_i32_i24_e32 v2, 0x400, v1
	v_sub_u32_e32 v0, v0, v2
	v_lshrrev_b32_e32 v2, 4, v0
	v_bitop3_b32 v0, v2, v0, 32 bitop3:0x6c
	v_ashrrev_i32_e32 v3, 31, v0
	v_lshrrev_b32_e32 v3, 26, v3
	v_lshlrev_b32_e32 v2, 3, v1
	v_add_u32_e32 v3, v0, v3
	v_and_b32_e32 v2, -16, v2
	v_ashrrev_i32_e32 v4, 6, v3
	s_mov_b32 s9, s89
	s_mov_b32 s8, s88
	v_add_u32_e32 v2, v4, v2
	v_and_b32_e32 v4, 3, v4
	s_lshl_b32 s88, s10, 8
	s_mov_b32 s89, s63
	s_mov_b64 s[22:23], s[90:91]
	v_and_or_b32 v4, v2, s5, v4
	s_lshl_b64 s[90:91], s[88:89], 1
	s_ashr_i32 s5, s48, 31
	s_mul_i32 s5, s90, s5
	s_mul_hi_u32 s6, s90, s48
	v_lshlrev_b32_e32 v1, 5, v1
	s_add_i32 s5, s6, s5
	s_bfe_u32 s6, s10, 0x10017
	v_and_b32_e32 v15, 32, v1
	v_and_b32_e32 v1, 0xffc0, v3
	s_mul_i32 s6, s6, s48
	v_sub_u32_e32 v0, v0, v1
	s_lshl_b32 s19, s24, 9
	s_add_i32 s5, s5, s6
	s_ashr_i32 s6, s40, 31
	v_lshrrev_b16_e32 v1, 7, v0
	s_mul_i32 s6, s19, s6
	s_mul_hi_u32 s7, s19, s40
	s_ashr_i32 s4, s3, 2
	v_and_b32_e32 v1, 1, v1
	s_lshl_b32 s18, s24, 8
	s_add_i32 s7, s7, s6
	s_mul_i32 s6, s19, s40
	v_add_u16_e32 v0, v0, v1
	v_lshlrev_b32_e32 v1, 1, v2
	v_lshrrev_b32_e32 v3, 2, v2
	s_add_u32 s38, s80, s6
	v_ashrrev_i16_sdwa v0, v239, sext(v0) dst_sel:DWORD dst_unused:UNUSED_PAD src0_sel:DWORD src1_sel:BYTE_0
	v_and_b32_e32 v1, 24, v1
	v_and_b32_e32 v3, 4, v3
	s_addc_u32 s39, s81, s7
	s_add_i32 s36, s83, 0
	v_bfe_i32 v16, v0, 0, 16
	v_or3_b32 v1, v4, v3, v1
	s_add_i32 m0, s36, 0x10000
	v_add_u32_e32 v0, v15, v16
	v_mul_lo_u32 v1, v1, s24
	global_load_lds_dwordx4 v142, s[38:39]
	s_add_i32 m0, s36, 0x12000
	v_add_lshl_u32 v146, v1, v0, 1
	s_add_u32 s6, s38, s18
	global_load_lds_dwordx4 v146, s[38:39]
	s_addc_u32 s7, s39, 0
	s_add_i32 m0, s36, 0x14000
	v_mul_lo_u32 v17, v2, s10
	s_mul_i32 s10, s90, s48
	global_load_lds_dwordx4 v142, s[6:7]
	s_add_i32 m0, s36, 0x16000
	s_add_u32 s98, s76, s10
	v_mov_b32_e32 v143, v177
	v_mov_b32_e32 v147, v177
	s_addc_u32 s99, s77, s5
	s_add_i32 s10, s36, 0x2000
	v_lshl_add_u64 v[4:5], s[6:7], 0, v[142:143]
	v_lshl_add_u64 v[6:7], s[6:7], 0, v[146:147]
	v_mov_b32_e32 v226, v4
	v_mov_b32_e32 v227, v5
	v_mov_b32_e32 v228, v6
	v_mov_b32_e32 v229, v7
	global_load_lds_dwordx4 v146, s[6:7]
	s_mov_b32 m0, s36
	s_add_u32 s6, s98, s88
	v_add_lshl_u32 v144, v0, v17, 1
	global_load_lds_dwordx4 v140, s[98:99]
	s_mov_b32 m0, s10
	s_addc_u32 s7, s99, 0
	s_add_i32 s11, s36, 0x4000
	global_load_lds_dwordx4 v144, s[98:99]
	s_mov_b32 m0, s11
	s_add_i32 s55, s36, 0x6000
	global_load_lds_dwordx4 v140, s[6:7]
	s_mov_b32 m0, s55
	v_mov_b32_e32 v141, v177
	global_load_lds_dwordx4 v144, s[6:7]
	v_mov_b32_e32 v145, v177
	s_cmp_eq_u32 s4, 1
	s_mov_b32 s29, s93
	s_mov_b32 s28, s92
	v_lshl_add_u64 v[0:1], s[38:39], 0, v[142:143]
	v_lshl_add_u64 v[2:3], s[38:39], 0, v[146:147]
	v_lshl_add_u64 v[8:9], s[98:99], 0, v[140:141]
	v_lshl_add_u64 v[10:11], s[98:99], 0, v[144:145]
	s_cselect_b64 s[92:93], -1, 0
	s_cmp_lg_u32 s4, 1
	s_cbranch_scc1 .LBB0_366
	s_barrier

; #define PG8_STAGE(bufoff, gbase, voff) do { _Pragma("unroll") for (int _i = 0; _i < 2; ++_i) \
;         __builtin_amdgcn_global_load_lds((const unsigned*)((const char*)(gbase) + (voff)[_i]), (PG8_LAS unsigned*)(lds + (bufoff) + ldsw + _i * 8192), 16, 0, 0); } while (0)
; #define PG8_LDA(dst, b, h) do { _Pragma("unroll") for (int m = 0; m < 4; ++m) _Pragma("unroll") for (int k = 0; k < 2; ++k) dst[m][k] = *(const PG8_LAS bf16x8*)(lds + PG8_SA(b, h) + aoff + m * 2048 + k * 1024); } while (0)
; #define PG8_LDB(dst, b, h) do { _Pragma("unroll") for (int n = 0; n < 2; ++n) _Pragma("unroll") for (int k = 0; k < 2; ++k) dst[n][k] = *(const PG8_LAS bf16x8*)(lds + PG8_SB(b, h) + boff + n * 2048 + k * 1024); } while (0)
; #define PG8_MMA(ai, bj, At, Bt) do { __builtin_amdgcn_s_setprio(1); _Pragma("unroll") for (int m = 0; m < 4; ++m) _Pragma("unroll") for (int n = 0; n < 2; ++n) _Pragma("unroll") for (int k = 0; k < 2; ++k) \
;         acc[ai][bj][m][n] = __builtin_amdgcn_mfma_f32_16x16x32_bf16(Bt[n][k], At[m][k], acc[ai][bj][m][n], 0, 0, 0); __builtin_amdgcn_s_setprio(0); } while (0)
; #define PG8_WAIT_V(n) asm volatile("s_waitcnt vmcnt(" #n ")" ::: "memory")
; #define PG8_WAIT_L(n) asm volatile("s_waitcnt lgkmcnt(" #n ")" ::: "memory")
; #define PG8_BAR __builtin_amdgcn_s_barrier()
; template <class Epi, class Sched, bool ALIGN_EPI = false, bool SP2 = false>
; __device__ __forceinline__ void gemm_phase(PG8_LAS unsigned char* lds, const Gemm g, const Sched& S, const Epi& E, const int wid_) {
;     ...
;         for (int t = 0; t < nt; t += 2) {
;             const bool last = (t == nt - 2);
;             const char* a1 = cA + (size_t)(t + 1) * kstep;
;             const char* a2 = last ? nA : cA + (size_t)(t + 2) * kstep; const char* b2 = last ? nB : cB + (size_t)(t + 2) * kstep;
;             const char* a3 = a2 + kstep; const char* b3 = b2 + kstep;
;             if (last && has_next) S.a_ready(nxt);
;             if constexpr (SP2) {
;             PG8_LDB(B0, 0, 0); PG8_LDB(B1, 0, 1); PG8_SCHED; PG8_LDA(At, 0, 0); PG8_STAGE(PG8_SA(1, 1), a1 + hstepA, voffA);
;             PG8_WAIT_V(8); PG8_WAIT_L(0); PG8_BAR; PG8_MMA(0, 0, At, B0); PG8_MMA(0, 1, At, B1); PG8_BAR; PG8_SCHED;
;             PG8_LDA(At, 0, 1); PG8_STAGE(PG8_SB(0, 0), b2, voffB); PG8_STAGE(PG8_SB(0, 1), b2 + hstepB, voffB); PG8_STAGE(PG8_SA(0, 0), a2, voffA);
.Lprio_a:
.LBB0_380:
	s_add_i32 s97, s38, 2
	s_add_u32 s98, s6, 0x80
	s_addc_u32 s39, s7, 0
	s_cmp_eq_u32 s41, s38
	s_cselect_b32 s39, s47, s39
	s_cselect_b32 s38, s46, s98
	s_cselect_b32 s99, s61, s62
	s_cselect_b32 s98, s60, s49
	s_add_i32 vcc_lo, 0, 0x14000
	v_add_u32_e32 v164, s42, v180
	v_add_u32_e32 v176, vcc_lo, v180
	ds_read_b128 v[128:131], v164
	ds_read_b128 v[132:135], v164 offset:1024
	ds_read_b128 v[136:139], v164 offset:2048
	ds_read_b128 v[164:167], v164 offset:3072
	ds_read_b128 v[168:171], v176
	ds_read_b128 v[172:175], v176 offset:1024
	ds_read_b128 v[182:185], v176 offset:2048
	ds_read_b128 v[186:189], v176 offset:3072
	v_lshl_add_u64 v[234:235], v[226:227], 0, s[66:67]
	s_add_i32 m0, s83, 0x1c000
	v_lshl_add_u64 v[226:227], v[228:229], 0, s[66:67]
	global_load_lds_dwordx4 v[234:235], off
	s_add_i32 m0, s83, 0x1e000
	s_nop 0
	global_load_lds_dwordx4 v[226:227], off
	v_lshl_add_u64 v[178:179], s[6:7], 0, v[162:163]
	s_add_i32 m0, s36, 0xc000
	ds_read_b128 v[190:193], v181
	ds_read_b128 v[194:197], v181 offset:1024
	ds_read_b128 v[198:201], v181 offset:2048
	ds_read_b128 v[202:205], v181 offset:3072
	ds_read_b128 v[206:209], v181 offset:4096
	ds_read_b128 v[212:215], v181 offset:5120
	ds_read_b128 v[216:219], v181 offset:6144
	ds_read_b128 v[220:223], v181 offset:7168
	global_load_lds_dwordx4 v[178:179], off
	v_lshl_add_u64 v[178:179], s[6:7], 0, v[160:161]
	s_add_i32 m0, s36, 0xe000
	s_nop 0
	global_load_lds_dwordx4 v[178:179], off
	s_waitcnt vmcnt(8)
	s_waitcnt lgkmcnt(0)
	s_barrier
	s_waitcnt lgkmcnt(0)
	v_mfma_f32_16x16x32_bf16 v[124:127], v[128:131], v[190:193], v[124:127]
	v_mfma_f32_16x16x32_bf16 v[120:123], v[136:139], v[190:193], v[120:123]
	v_mfma_f32_16x16x32_bf16 v[116:119], v[128:131], v[198:201], v[116:119]
	v_mfma_f32_16x16x32_bf16 v[112:115], v[136:139], v[198:201], v[112:115]
	v_mfma_f32_16x16x32_bf16 v[100:103], v[128:131], v[206:209], v[100:103]
	v_mfma_f32_16x16x32_bf16 v[96:99], v[136:139], v[206:209], v[96:99]
	v_mfma_f32_16x16x32_bf16 v[84:87], v[128:131], v[216:219], v[84:87]
	v_mfma_f32_16x16x32_bf16 v[80:83], v[136:139], v[216:219], v[80:83]
	v_mfma_f32_16x16x32_bf16 v[124:127], v[132:135], v[194:197], v[124:127]
	v_mfma_f32_16x16x32_bf16 v[120:123], v[164:167], v[194:197], v[120:123]
	v_mfma_f32_16x16x32_bf16 v[116:119], v[132:135], v[202:205], v[116:119]
	v_mfma_f32_16x16x32_bf16 v[112:115], v[164:167], v[202:205], v[112:115]
	v_mfma_f32_16x16x32_bf16 v[100:103], v[132:135], v[212:215], v[100:103]
	v_mfma_f32_16x16x32_bf16 v[96:99], v[164:167], v[212:215], v[96:99]
	v_mfma_f32_16x16x32_bf16 v[84:87], v[132:135], v[220:223], v[84:87]
	v_mfma_f32_16x16x32_bf16 v[80:83], v[164:167], v[220:223], v[80:83]
	v_mfma_f32_16x16x32_bf16 v[108:111], v[168:171], v[190:193], v[108:111]
	v_mfma_f32_16x16x32_bf16 v[104:107], v[182:185], v[190:193], v[104:107]
	v_mfma_f32_16x16x32_bf16 v[92:95], v[168:171], v[198:201], v[92:95]
	v_mfma_f32_16x16x32_bf16 v[88:91], v[182:185], v[198:201], v[88:91]
	v_mfma_f32_16x16x32_bf16 v[76:79], v[168:171], v[206:209], v[76:79]
	v_mfma_f32_16x16x32_bf16 v[72:75], v[182:185], v[206:209], v[72:75]
	v_mfma_f32_16x16x32_bf16 v[68:71], v[168:171], v[216:219], v[68:71]
	v_mfma_f32_16x16x32_bf16 v[64:67], v[182:185], v[216:219], v[64:67]
	v_mfma_f32_16x16x32_bf16 v[108:111], v[172:175], v[194:197], v[108:111]
	v_mfma_f32_16x16x32_bf16 v[104:107], v[186:189], v[194:197], v[104:107]
	v_mfma_f32_16x16x32_bf16 v[92:95], v[172:175], v[202:205], v[92:95]
	v_mfma_f32_16x16x32_bf16 v[88:91], v[186:189], v[202:205], v[88:91]
	v_mfma_f32_16x16x32_bf16 v[76:79], v[172:175], v[212:215], v[76:79]
	v_mfma_f32_16x16x32_bf16 v[72:75], v[186:189], v[212:215], v[72:75]
	v_mfma_f32_16x16x32_bf16 v[68:71], v[172:175], v[220:223], v[68:71]
	v_mfma_f32_16x16x32_bf16 v[64:67], v[186:189], v[220:223], v[64:67]
	s_barrier
	s_add_i32 vcc_hi, s42, s83
	v_lshl_add_u64 v[178:179], s[98:99], 0, v[142:143]
	s_mov_b32 m0, vcc_hi
	ds_read_b128 v[190:193], v181 offset:16384
	ds_read_b128 v[194:197], v181 offset:17408
	ds_read_b128 v[198:201], v181 offset:18432
	ds_read_b128 v[202:205], v181 offset:19456
	ds_read_b128 v[206:209], v181 offset:20480
	ds_read_b128 v[212:215], v181 offset:21504
	ds_read_b128 v[216:219], v181 offset:22528
	ds_read_b128 v[220:223], v181 offset:23552
	global_load_lds_dwordx4 v[178:179], off
	s_add_i32 m0, vcc_hi, 0x2000
	v_lshl_add_u64 v[224:225], s[98:99], 0, v[146:147]
	s_add_u32 s98, s98, s18
	s_addc_u32 s99, s99, 0
	s_add_i32 vcc_lo, vcc_lo, s83
	global_load_lds_dwordx4 v[224:225], off
	v_lshl_add_u64 v[226:227], s[98:99], 0, v[142:143]
	v_lshl_add_u64 v[228:229], s[98:99], 0, v[146:147]
	v_lshl_add_u64 v[230:231], s[38:39], 0, v[140:141]
	s_mov_b32 m0, s36
	v_lshl_add_u64 v[232:233], s[38:39], 0, v[144:145]
	global_load_lds_dwordx4 v[230:231], off
	s_mov_b32 m0, s10
	s_nop 0
	global_load_lds_dwordx4 v[232:233], off
	s_waitcnt vmcnt(6)
	s_waitcnt lgkmcnt(0)
	s_barrier
; #define PG8_STAGE(bufoff, gbase, voff) do { _Pragma("unroll") for (int _i = 0; _i < 2; ++_i) \
;         __builtin_amdgcn_global_load_lds((const unsigned*)((const char*)(gbase) + (voff)[_i]), (PG8_LAS unsigned*)(lds + (bufoff) + ldsw + _i * 8192), 16, 0, 0); } while (0)
; #define PG8_LDA(dst, b, h) do { _Pragma("unroll") for (int m = 0; m < 4; ++m) _Pragma("unroll") for (int k = 0; k < 2; ++k) dst[m][k] = *(const PG8_LAS bf16x8*)(lds + PG8_SA(b, h) + aoff + m * 2048 + k * 1024); } while (0)
; #define PG8_LDB(dst, b, h) do { _Pragma("unroll") for (int n = 0; n < 2; ++n) _Pragma("unroll") for (int k = 0; k < 2; ++k) dst[n][k] = *(const PG8_LAS bf16x8*)(lds + PG8_SB(b, h) + boff + n * 2048 + k * 1024); } while (0)
; #define PG8_MMA(ai, bj, At, Bt) do { __builtin_amdgcn_s_setprio(1); _Pragma("unroll") for (int m = 0; m < 4; ++m) _Pragma("unroll") for (int n = 0; n < 2; ++n) _Pragma("unroll") for (int k = 0; k < 2; ++k) \
;         acc[ai][bj][m][n] = __builtin_amdgcn_mfma_f32_16x16x32_bf16(Bt[n][k], At[m][k], acc[ai][bj][m][n], 0, 0, 0); __builtin_amdgcn_s_setprio(0); } while (0)
; #define PG8_WAIT_V(n) asm volatile("s_waitcnt vmcnt(" #n ")" ::: "memory")
; #define PG8_WAIT_L(n) asm volatile("s_waitcnt lgkmcnt(" #n ")" ::: "memory")
; #define PG8_BAR __builtin_amdgcn_s_barrier()
; #define PG8_SCHED __builtin_amdgcn_sched_barrier(0)
; template <class Epi, class Sched, bool ALIGN_EPI = false, bool SP2 = false>
; __device__ __forceinline__ void gemm_phase(PG8_LAS unsigned char* lds, const Gemm g, const Sched& S, const Epi& E, const int wid_) {
;     ...
;             PG8_WAIT_V(8); PG8_WAIT_L(0); PG8_BAR; PG8_MMA(1, 0, At, B0); PG8_MMA(1, 1, At, B1); PG8_BAR; PG8_SCHED;
;             PG8_LDB(B0, 1, 0); PG8_LDB(B1, 1, 1); PG8_SCHED; PG8_LDA(At, 1, 0); PG8_STAGE(PG8_SA(0, 1), a2 + hstepA, voffA);
;             PG8_WAIT_V(8); PG8_WAIT_L(0); PG8_BAR; PG8_MMA(0, 0, At, B0); PG8_MMA(0, 1, At, B1); PG8_BAR; PG8_SCHED;
	s_waitcnt lgkmcnt(0)
	v_mfma_f32_16x16x32_bf16 v[60:63], v[128:131], v[190:193], v[60:63]
	v_mfma_f32_16x16x32_bf16 v[56:59], v[136:139], v[190:193], v[56:59]
	v_mfma_f32_16x16x32_bf16 v[52:55], v[128:131], v[198:201], v[52:55]
	v_mfma_f32_16x16x32_bf16 v[48:51], v[136:139], v[198:201], v[48:51]
	v_mfma_f32_16x16x32_bf16 v[36:39], v[128:131], v[206:209], v[36:39]
	v_mfma_f32_16x16x32_bf16 v[32:35], v[136:139], v[206:209], v[32:35]
	v_mfma_f32_16x16x32_bf16 v[20:23], v[128:131], v[216:219], v[20:23]
	v_mfma_f32_16x16x32_bf16 v[16:19], v[136:139], v[216:219], v[16:19]
	v_mfma_f32_16x16x32_bf16 v[60:63], v[132:135], v[194:197], v[60:63]
	v_mfma_f32_16x16x32_bf16 v[56:59], v[164:167], v[194:197], v[56:59]
	v_mfma_f32_16x16x32_bf16 v[52:55], v[132:135], v[202:205], v[52:55]
	v_mfma_f32_16x16x32_bf16 v[48:51], v[164:167], v[202:205], v[48:51]
	v_mfma_f32_16x16x32_bf16 v[36:39], v[132:135], v[212:215], v[36:39]
	v_mfma_f32_16x16x32_bf16 v[32:35], v[164:167], v[212:215], v[32:35]
	v_mfma_f32_16x16x32_bf16 v[20:23], v[132:135], v[220:223], v[20:23]
	v_mfma_f32_16x16x32_bf16 v[16:19], v[164:167], v[220:223], v[16:19]
	v_mfma_f32_16x16x32_bf16 v[44:47], v[168:171], v[190:193], v[44:47]
	v_mfma_f32_16x16x32_bf16 v[40:43], v[182:185], v[190:193], v[40:43]
	v_mfma_f32_16x16x32_bf16 v[28:31], v[168:171], v[198:201], v[28:31]
	v_mfma_f32_16x16x32_bf16 v[24:27], v[182:185], v[198:201], v[24:27]
	v_mfma_f32_16x16x32_bf16 v[12:15], v[168:171], v[206:209], v[12:15]
	v_mfma_f32_16x16x32_bf16 v[8:11], v[182:185], v[206:209], v[8:11]
	v_mfma_f32_16x16x32_bf16 v[4:7], v[168:171], v[216:219], v[4:7]
	v_mfma_f32_16x16x32_bf16 v[0:3], v[182:185], v[216:219], v[0:3]
	v_mfma_f32_16x16x32_bf16 v[44:47], v[172:175], v[194:197], v[44:47]
	v_mfma_f32_16x16x32_bf16 v[40:43], v[186:189], v[194:197], v[40:43]
	v_mfma_f32_16x16x32_bf16 v[28:31], v[172:175], v[202:205], v[28:31]
	v_mfma_f32_16x16x32_bf16 v[24:27], v[186:189], v[202:205], v[24:27]
	v_mfma_f32_16x16x32_bf16 v[12:15], v[172:175], v[212:215], v[12:15]
	v_mfma_f32_16x16x32_bf16 v[8:11], v[186:189], v[212:215], v[8:11]
	v_mfma_f32_16x16x32_bf16 v[4:7], v[172:175], v[220:223], v[4:7]
	v_mfma_f32_16x16x32_bf16 v[0:3], v[186:189], v[220:223], v[0:3]
	s_barrier
	s_add_i32 s98, 0, 0x18000
	s_add_i32 s99, 0, 0x1c000
	v_add_u32_e32 v164, s98, v180
	v_add_u32_e32 v176, s99, v180
	ds_read_b128 v[128:131], v164
	ds_read_b128 v[132:135], v164 offset:1024
	ds_read_b128 v[136:139], v164 offset:2048
	ds_read_b128 v[164:167], v164 offset:3072
	ds_read_b128 v[168:171], v176
	ds_read_b128 v[172:175], v176 offset:1024
	ds_read_b128 v[182:185], v176 offset:2048
	ds_read_b128 v[186:189], v176 offset:3072
	s_add_u32 s38, s38, s88
	s_addc_u32 s39, s39, 0
	s_add_i32 m0, s83, 0x14000
	s_nop 0
	global_load_lds_dwordx4 v[226:227], off
	s_add_i32 m0, s83, 0x16000
	s_nop 0
	global_load_lds_dwordx4 v[228:229], off
	s_mov_b32 m0, s11
	v_lshl_add_u64 v[234:235], s[38:39], 0, v[140:141]
	ds_read_b128 v[190:193], v181 offset:32768
	ds_read_b128 v[194:197], v181 offset:33792
	ds_read_b128 v[198:201], v181 offset:34816
	ds_read_b128 v[202:205], v181 offset:35840
	ds_read_b128 v[206:209], v181 offset:36864
	ds_read_b128 v[212:215], v181 offset:37888
	ds_read_b128 v[216:219], v181 offset:38912
	ds_read_b128 v[220:223], v181 offset:39936
	global_load_lds_dwordx4 v[234:235], off
	v_lshl_add_u64 v[234:235], s[38:39], 0, v[144:145]
	s_mov_b32 m0, s55
	s_nop 0
	global_load_lds_dwordx4 v[234:235], off
	s_waitcnt vmcnt(8)
	s_waitcnt lgkmcnt(0)
	s_barrier
	s_waitcnt lgkmcnt(0)
	v_mfma_f32_16x16x32_bf16 v[124:127], v[128:131], v[190:193], v[124:127]
	v_mfma_f32_16x16x32_bf16 v[120:123], v[136:139], v[190:193], v[120:123]
	v_mfma_f32_16x16x32_bf16 v[116:119], v[128:131], v[198:201], v[116:119]
	v_mfma_f32_16x16x32_bf16 v[112:115], v[136:139], v[198:201], v[112:115]
	v_mfma_f32_16x16x32_bf16 v[100:103], v[128:131], v[206:209], v[100:103]
	v_mfma_f32_16x16x32_bf16 v[96:99], v[136:139], v[206:209], v[96:99]
	v_mfma_f32_16x16x32_bf16 v[84:87], v[128:131], v[216:219], v[84:87]
	v_mfma_f32_16x16x32_bf16 v[80:83], v[136:139], v[216:219], v[80:83]
	v_mfma_f32_16x16x32_bf16 v[124:127], v[132:135], v[194:197], v[124:127]
	v_mfma_f32_16x16x32_bf16 v[120:123], v[164:167], v[194:197], v[120:123]
	v_mfma_f32_16x16x32_bf16 v[116:119], v[132:135], v[202:205], v[116:119]
	v_mfma_f32_16x16x32_bf16 v[112:115], v[164:167], v[202:205], v[112:115]
	v_mfma_f32_16x16x32_bf16 v[100:103], v[132:135], v[212:215], v[100:103]
	v_mfma_f32_16x16x32_bf16 v[96:99], v[164:167], v[212:215], v[96:99]
	v_mfma_f32_16x16x32_bf16 v[84:87], v[132:135], v[220:223], v[84:87]
	v_mfma_f32_16x16x32_bf16 v[80:83], v[164:167], v[220:223], v[80:83]
	v_mfma_f32_16x16x32_bf16 v[108:111], v[168:171], v[190:193], v[108:111]
	v_mfma_f32_16x16x32_bf16 v[104:107], v[182:185], v[190:193], v[104:107]
	v_mfma_f32_16x16x32_bf16 v[92:95], v[168:171], v[198:201], v[92:95]
	v_mfma_f32_16x16x32_bf16 v[88:91], v[182:185], v[198:201], v[88:91]
	v_mfma_f32_16x16x32_bf16 v[76:79], v[168:171], v[206:209], v[76:79]
	v_mfma_f32_16x16x32_bf16 v[72:75], v[182:185], v[206:209], v[72:75]
	v_mfma_f32_16x16x32_bf16 v[68:71], v[168:171], v[216:219], v[68:71]
	v_mfma_f32_16x16x32_bf16 v[64:67], v[182:185], v[216:219], v[64:67]
	v_mfma_f32_16x16x32_bf16 v[108:111], v[172:175], v[194:197], v[108:111]
	v_mfma_f32_16x16x32_bf16 v[104:107], v[186:189], v[194:197], v[104:107]
	v_mfma_f32_16x16x32_bf16 v[92:95], v[172:175], v[202:205], v[92:95]
	v_mfma_f32_16x16x32_bf16 v[88:91], v[186:189], v[202:205], v[88:91]
	v_mfma_f32_16x16x32_bf16 v[76:79], v[172:175], v[212:215], v[76:79]
	v_mfma_f32_16x16x32_bf16 v[72:75], v[186:189], v[212:215], v[72:75]
	v_mfma_f32_16x16x32_bf16 v[68:71], v[172:175], v[220:223], v[68:71]
	v_mfma_f32_16x16x32_bf16 v[64:67], v[186:189], v[220:223], v[64:67]
	s_barrier
; #define PG8_STAGE(bufoff, gbase, voff) do { _Pragma("unroll") for (int _i = 0; _i < 2; ++_i) \
;         __builtin_amdgcn_global_load_lds((const unsigned*)((const char*)(gbase) + (voff)[_i]), (PG8_LAS unsigned*)(lds + (bufoff) + ldsw + _i * 8192), 16, 0, 0); } while (0)
; #define PG8_LDA(dst, b, h) do { _Pragma("unroll") for (int m = 0; m < 4; ++m) _Pragma("unroll") for (int k = 0; k < 2; ++k) dst[m][k] = *(const PG8_LAS bf16x8*)(lds + PG8_SA(b, h) + aoff + m * 2048 + k * 1024); } while (0)
; #define PG8_MMA(ai, bj, At, Bt) do { __builtin_amdgcn_s_setprio(1); _Pragma("unroll") for (int m = 0; m < 4; ++m) _Pragma("unroll") for (int n = 0; n < 2; ++n) _Pragma("unroll") for (int k = 0; k < 2; ++k) \
;         acc[ai][bj][m][n] = __builtin_amdgcn_mfma_f32_16x16x32_bf16(Bt[n][k], At[m][k], acc[ai][bj][m][n], 0, 0, 0); __builtin_amdgcn_s_setprio(0); } while (0)
; #define PG8_WAIT_V(n) asm volatile("s_waitcnt vmcnt(" #n ")" ::: "memory")
; #define PG8_WAIT_L(n) asm volatile("s_waitcnt lgkmcnt(" #n ")" ::: "memory")
; #define PG8_BAR __builtin_amdgcn_s_barrier()
; #define PG8_SCHED __builtin_amdgcn_sched_barrier(0)
; template <class Epi, class Sched, bool ALIGN_EPI = false, bool SP2 = false>
; __device__ __forceinline__ void gemm_phase(PG8_LAS unsigned char* lds, const Gemm g, const Sched& S, const Epi& E, const int wid_) {
;     ...
;             PG8_LDA(At, 1, 1); PG8_STAGE(PG8_SB(1, 0), b3, voffB); PG8_STAGE(PG8_SB(1, 1), b3 + hstepB, voffB); PG8_STAGE(PG8_SA(1, 0), a3, voffA);
;             PG8_WAIT_V(8); PG8_WAIT_L(0); PG8_BAR; PG8_MMA(1, 0, At, B0); PG8_MMA(1, 1, At, B1); PG8_BAR; PG8_SCHED;
;     ...
;         if constexpr (ALIGN_EPI) { if (wr == 0) PG8_BAR; }
	s_add_i32 s38, s98, s83
	v_lshl_add_u64 v[178:179], v[178:179], 0, s[66:67]
	s_mov_b32 m0, s38
	ds_read_b128 v[190:193], v181 offset:49152
	ds_read_b128 v[194:197], v181 offset:50176
	ds_read_b128 v[198:201], v181 offset:51200
	ds_read_b128 v[202:205], v181 offset:52224
	ds_read_b128 v[206:209], v181 offset:53248
	ds_read_b128 v[212:215], v181 offset:54272
	ds_read_b128 v[216:219], v181 offset:55296
	ds_read_b128 v[220:223], v181 offset:56320
	global_load_lds_dwordx4 v[178:179], off
	v_lshl_add_u64 v[178:179], v[224:225], 0, s[66:67]
	s_add_i32 m0, s38, 0x2000
	s_add_i32 s38, s99, s83
	global_load_lds_dwordx4 v[178:179], off
	v_lshl_add_u64 v[178:179], v[230:231], 0, s[66:67]
	s_mov_b32 m0, s33
	s_nop 0
	global_load_lds_dwordx4 v[178:179], off
	v_lshl_add_u64 v[178:179], v[232:233], 0, s[66:67]
	s_mov_b32 m0, s52
	s_nop 0
	global_load_lds_dwordx4 v[178:179], off
	s_waitcnt vmcnt(6)
	s_waitcnt lgkmcnt(0)
	s_barrier
	s_waitcnt lgkmcnt(0)
	v_mfma_f32_16x16x32_bf16 v[60:63], v[128:131], v[190:193], v[60:63]
	v_mfma_f32_16x16x32_bf16 v[56:59], v[136:139], v[190:193], v[56:59]
	v_mfma_f32_16x16x32_bf16 v[52:55], v[128:131], v[198:201], v[52:55]
	v_mfma_f32_16x16x32_bf16 v[48:51], v[136:139], v[198:201], v[48:51]
	v_mfma_f32_16x16x32_bf16 v[36:39], v[128:131], v[206:209], v[36:39]
	v_mfma_f32_16x16x32_bf16 v[32:35], v[136:139], v[206:209], v[32:35]
	v_mfma_f32_16x16x32_bf16 v[20:23], v[128:131], v[216:219], v[20:23]
	v_mfma_f32_16x16x32_bf16 v[16:19], v[136:139], v[216:219], v[16:19]
	v_mfma_f32_16x16x32_bf16 v[60:63], v[132:135], v[194:197], v[60:63]
	v_mfma_f32_16x16x32_bf16 v[56:59], v[164:167], v[194:197], v[56:59]
	v_mfma_f32_16x16x32_bf16 v[52:55], v[132:135], v[202:205], v[52:55]
	v_mfma_f32_16x16x32_bf16 v[48:51], v[164:167], v[202:205], v[48:51]
	v_mfma_f32_16x16x32_bf16 v[36:39], v[132:135], v[212:215], v[36:39]
	v_mfma_f32_16x16x32_bf16 v[32:35], v[164:167], v[212:215], v[32:35]
	v_mfma_f32_16x16x32_bf16 v[20:23], v[132:135], v[220:223], v[20:23]
	v_mfma_f32_16x16x32_bf16 v[16:19], v[164:167], v[220:223], v[16:19]
	v_mfma_f32_16x16x32_bf16 v[44:47], v[168:171], v[190:193], v[44:47]
	v_mfma_f32_16x16x32_bf16 v[40:43], v[182:185], v[190:193], v[40:43]
	v_mfma_f32_16x16x32_bf16 v[28:31], v[168:171], v[198:201], v[28:31]
	v_mfma_f32_16x16x32_bf16 v[24:27], v[182:185], v[198:201], v[24:27]
	v_mfma_f32_16x16x32_bf16 v[12:15], v[168:171], v[206:209], v[12:15]
	v_mfma_f32_16x16x32_bf16 v[8:11], v[182:185], v[206:209], v[8:11]
	v_mfma_f32_16x16x32_bf16 v[4:7], v[168:171], v[216:219], v[4:7]
	v_mfma_f32_16x16x32_bf16 v[0:3], v[182:185], v[216:219], v[0:3]
	v_mfma_f32_16x16x32_bf16 v[44:47], v[172:175], v[194:197], v[44:47]
	v_mfma_f32_16x16x32_bf16 v[40:43], v[186:189], v[194:197], v[40:43]
	v_mfma_f32_16x16x32_bf16 v[28:31], v[172:175], v[202:205], v[28:31]
	v_mfma_f32_16x16x32_bf16 v[24:27], v[186:189], v[202:205], v[24:27]
	v_mfma_f32_16x16x32_bf16 v[12:15], v[172:175], v[212:215], v[12:15]
	v_mfma_f32_16x16x32_bf16 v[8:11], v[186:189], v[212:215], v[8:11]
	v_mfma_f32_16x16x32_bf16 v[4:7], v[172:175], v[220:223], v[4:7]
	v_mfma_f32_16x16x32_bf16 v[0:3], v[186:189], v[220:223], v[0:3]
	s_barrier
	s_add_u32 s49, s49, 0x100
	s_addc_u32 s62, s62, 0
	s_add_u32 s6, s6, 0x100
	s_addc_u32 s7, s7, 0
	s_cmp_ge_u32 s97, s71
	s_mov_b32 s38, s97
	s_cbranch_scc0 .LBB0_380
	s_setprio 0
	s_and_b64 vcc, exec, s[94:95]
	s_cbranch_vccz .LBB0_384
	s_barrier
	v_lshl_add_u32 v164, s48, 8, v153
	s_cmp_lt_i32 s37, 2
	s_mov_b64 s[6:7], -1
	s_cbranch_scc0 .LBB0_385
